# DSA: V tile LDS row pitch 288 -> 320 bytes (transposed reads were 2-way bank conflicted on the 64-bank LDS), output-transpose regions moved into the K/V buffers behind a run-start barrier
# baseline (speedup 1.0000x reference)
; #define LAS __attribute__((address_space(3)))
; #define LDS_WAIT() asm volatile("s_waitcnt lgkmcnt(0)" ::: "memory")
; __device__ __forceinline__ void dsa_unit(const bf16* QB, const int* SEL, bf16* AO, int b, int kvh, int t, LAS unsigned char* wl, int lane) {
;     const size_t rowbase = (size_t)b * SEQ, row = rowbase + t;
;     const int n = lane & 31, hi = lane >> 5, l15 = lane & 15, kq = lane >> 4;
;     const int ce = ((t >> 6) + 1) << 6; const int nsel = ce < 256 ? ce : 256;
;     LAS unsigned char* buf = wl;
;     LAS bf16* pT = (LAS bf16*)(wl + 9216);
;     LAS int* il = (LAS int*)(wl + 11264);
;     const LAS float* bl = (const LAS float*)(wl + 12288) + kvh * 128;
; __global__ void __launch_bounds__(NWAVES * 64, 2) fwd_megakernel(Args args) {
;     ...
;                 { LAS float* blw = (LAS float*)(wl + 12288);
; #pragma unroll
;                   for (int i = 0; i < 8; ++i) blw[lane + 64 * i] = LOG2E * args.in[I_RELB][lane + 64 * i];
;                   LDS_WAIT(); }
.Ldsa_new:
	v_readfirstlane_b32 s0, v207
	v_readlane_b32 s1, v251, 14
	v_readlane_b32 s12, v251, 0
	v_readlane_b32 s13, v251, 1
	s_lshr_b32 s0, s0, 6
	s_lshr_b32 s2, s84, 3
	s_mov_b32 s16, 0x88000
	s_mov_b32 s17, 0
	s_movk_i32 s23, 0x2200
	v_lshlrev_b32_e32 v178, 2, v207
	s_nop 4
	global_load_dword v179, v178, s[12:13]
	v_and_b32_e32 v64, 31, v206
	v_lshrrev_b32_e32 v65, 5, v206
	v_lshlrev_b32_e32 v175, 3, v65
	v_and_b32_e32 v66, 19, v64
	v_lshrrev_b32_e32 v67, 1, v64
	v_and_b32_e32 v67, 4, v67
	v_lshlrev_b32_e32 v68, 1, v64
	v_and_b32_e32 v68, 8, v68
	v_or3_b32 v66, v66, v67, v68
	v_mul_u32_u24_e32 v66, 0x110, v66
	v_lshl_add_u32 v66, v65, 4, v66
	v_add_u32_e32 v164, 0x5000, v66
	v_bfe_u32 v66, v206, 2, 2
	v_or_b32_e32 v66, v175, v66
	v_mul_u32_u24_e32 v66, 0x140, v66
	v_and_b32_e32 v67, 16, v206
	v_and_b32_e32 v68, 3, v206
	v_lshl_or_b32 v67, v68, 2, v67
	v_lshl_add_u32 v165, v67, 1, v66
	v_lshrrev_b32_e32 v66, 4, v207
	v_and_b32_e32 v67, 15, v207
	v_lshlrev_b32_e32 v67, 4, v67
	v_mul_u32_u24_e32 v68, 0x110, v66
	v_add_u32_e32 v68, v68, v67
	v_add_u32_e32 v166, 0x5000, v68
	v_mul_u32_u24_e32 v68, 0x140, v66
	v_add_u32_e32 v167, v68, v67
	s_waitcnt vmcnt(0)
	v_mul_f32_e32 v179, 0x3fb8aa3b, v179
	v_add_u32_e32 v178, 0x1a800, v178
	ds_write_b32 v178, v179
	v_readlane_b32 s46, v251, 19
	v_readlane_b32 s47, v251, 20
	s_mul_i32 s45, s0, 0x2200
	s_lshl_b32 s44, s0, 3
	s_waitcnt lgkmcnt(0)
	s_barrier
	s_mov_b32 s3, s1

; #define LAS __attribute__((address_space(3)))
; #define LDS_WAIT() asm volatile("s_waitcnt lgkmcnt(0)" ::: "memory")
; __device__ __forceinline__ void dsa_unit(const bf16* QB, const int* SEL, bf16* AO, int b, int kvh, int t, LAS unsigned char* wl, int lane) {
;     ...
;     int sidx[8];
; #pragma unroll
;     for (int kb = 0; kb < 8; ++kb) { const int p = 32 * kb + n; sidx[kb] = (p < nsel) ? SEL[row * 256 + p] : 0; }
;     bf16x8 qf[4];
;     { const bf16* qp = QB + row * NBP + CQ + (kvh * 4 + (l15 & 3)) * 128 + 8 * kq;
; #pragma unroll
;       for (int ks = 0; ks < 4; ++ks) qf[ks] = *(const bf16x8*)(qp + 32 * ks); }
;     if (hi == 0) {
; #pragma unroll
;         for (int kb = 0; kb < 8; ++kb) il[32 * kb + n] = sidx[kb];
;     }
;     LDS_WAIT();
;     const int r4 = kq, c16 = l15;
;     const bf16* kg = QB + rowbase * NBP + CK + kvh * 128 + c16 * 8;
;     const bf16* vg = QB + rowbase * NBP + CV + kvh * 128 + c16 * 8;
;     bf16x8 kr[3][8];
; #pragma unroll
;     for (int pb = 0; pb < 3; ++pb)
; #pragma unroll
;         for (int i = 0; i < 8; ++i) kr[pb][i] = *(const bf16x8*)(kg + (size_t)il[32 * pb + 4 * i + r4] * NBP);
;     float lg[8][4];
;     float mx[4] = {-__builtin_inff(), -__builtin_inff(), -__builtin_inff(), -__builtin_inff()};
;     LAS unsigned char* kdst = buf + r4 * 272 + c16 * 16;
;     const LAS unsigned char* kfb = buf + l15 * 272 + 16 * kq;
.Ldsa_selld_end:
	v_mov_b32_e32 v64, 0
	v_mov_b32_e32 v65, 0
	v_mov_b32_e32 v66, 0
	v_mov_b32_e32 v67, 0
	v_lshlrev_b32_e32 v179, 6, v206
	s_lshl_b32 s24, s0, 12
	s_add_u32 s24, s24, 0x12800
	v_add_u32_e32 v179, s24, v179
	ds_write_b128 v179, v[64:67] offset:0
	ds_write_b128 v179, v[64:67] offset:16
	ds_write_b128 v179, v[64:67] offset:32
	ds_write_b128 v179, v[64:67] offset:48
	v_lshrrev_b32_e32 v178, 4, v207
	v_add_u32_e32 v178, s4, v178
	v_and_b32_e32 v179, 15, v207
	v_lshlrev_b32_e32 v182, 4, v179
	s_lshl_b32 s24, s5, 8
	s_add_u32 s24, s24, 0x1000
	v_add_u32_e32 v182, s24, v182
	v_lshl_add_u64 v[160:161], s[78:79], 0, v[182:183]
	v_mad_u64_u32 v[160:161], s[12:13], v178, s23, v[160:161]
	s_mov_b32 s24, 0x44000
	s_mov_b32 s25, 0
	v_lshl_add_u64 v[162:163], v[160:161], 0, s[24:25]
	global_load_dwordx4 v[144:147], v[160:161], off
	global_load_dwordx4 v[148:151], v[160:161], off offset:1024
	global_load_dwordx4 v[152:155], v[162:163], off
	global_load_dwordx4 v[156:159], v[162:163], off offset:1024
	v_lshl_add_u64 v[160:161], v[160:161], 0, s[16:17]
	v_lshl_add_u64 v[162:163], v[162:163], 0, s[16:17]
	v_and_b32_e32 v64, 31, v206
	v_lshrrev_b32_e32 v65, 2, v64
	v_and_b32_e32 v66, 3, v64
	s_add_u32 s24, s44, s7
	s_add_u32 s24, s24, s4
	v_add_u32_e32 v178, s24, v65
	s_lshl_b32 s25, s5, 2
	v_add_u32_e32 v179, s25, v66
	v_lshlrev_b32_e32 v179, 8, v179
	v_lshl_add_u32 v182, v175, 1, v179
	v_lshl_add_u64 v[128:129], s[78:79], 0, v[182:183]
	v_mad_u64_u32 v[128:129], s[12:13], v178, s23, v[128:129]
	global_load_dwordx4 v[80:83], v[128:129], off offset:0
	global_load_dwordx4 v[84:87], v[128:129], off offset:32
	global_load_dwordx4 v[88:91], v[128:129], off offset:64
	global_load_dwordx4 v[92:95], v[128:129], off offset:96
	global_load_dwordx4 v[96:99], v[128:129], off offset:128
	global_load_dwordx4 v[100:103], v[128:129], off offset:160
	global_load_dwordx4 v[104:107], v[128:129], off offset:192
	global_load_dwordx4 v[108:111], v[128:129], off offset:224
	v_add_u32_e32 v178, s44, v65
	v_lshlrev_b32_e32 v172, 9, v178
	v_add_u32_e32 v172, 0x12800, v172
	s_add_u32 s24, s44, s7
	v_add_u32_e32 v178, s24, v65
	v_sub_u32_e32 v178, v175, v178
	v_add_u32_e32 v178, 0x80, v178
	v_lshlrev_b32_e32 v178, 2, v178
	v_lshl_add_u32 v177, v66, 10, v178
	v_add_u32_e32 v177, 0x1b400, v177
	s_sub_u32 s19, s24, 0x7a
	s_lshl_b32 s25, s5, 2
	v_add_u32_e32 v178, s25, v66
	v_lshlrev_b32_e32 v178, 7, v178
	v_add_u32_e32 v176, 0x1a83c, v178
	ds_read_b32 v176, v176
	v_and_b32_e32 v64, 0xff, v207
	v_subrev_u32_e32 v65, 0x80, v64
	v_sub_u32_e32 v66, 0, v65
	v_max_i32_e32 v66, v65, v66
	v_mov_b32_e32 v67, 8
	v_cmp_le_i32_e32 vcc, 12, v66
	s_nop 1
	v_addc_co_u32_e32 v67, vcc, 0, v67, vcc
	v_cmp_le_i32_e32 vcc, 16, v66
	s_nop 1
	v_addc_co_u32_e32 v67, vcc, 0, v67, vcc
	v_cmp_le_i32_e32 vcc, 23, v66
	s_nop 1
	v_addc_co_u32_e32 v67, vcc, 0, v67, vcc
	v_cmp_le_i32_e32 vcc, 32, v66
	s_nop 1
	v_addc_co_u32_e32 v67, vcc, 0, v67, vcc
	v_cmp_le_i32_e32 vcc, 46, v66
	s_nop 1
	v_addc_co_u32_e32 v67, vcc, 0, v67, vcc
	v_cmp_le_i32_e32 vcc, 64, v66
	s_nop 1
	v_addc_co_u32_e32 v67, vcc, 0, v67, vcc
	v_cmp_le_i32_e32 vcc, 91, v66
	s_nop 1
	v_addc_co_u32_e32 v67, vcc, 0, v67, vcc
	v_cmp_gt_i32_e32 vcc, 8, v66
	s_nop 1
	v_cndmask_b32_e32 v67, v67, v66, vcc
	v_add_u32_e32 v68, 16, v67
	v_cmp_lt_i32_e32 vcc, 0, v65
	s_nop 1
	v_cndmask_b32_e32 v67, v67, v68, vcc
	v_lshrrev_b32_e32 v68, 8, v207
	s_lshl_b32 s24, s5, 2
	v_add_u32_e32 v69, s24, v68
	v_lshl_add_u32 v69, v69, 5, v67
	v_lshlrev_b32_e32 v69, 2, v69
	v_add_u32_e32 v69, 0x1a800, v69
	ds_read_b32 v70, v69
	ds_read_b32 v71, v69 offset:256
	v_lshl_add_u32 v72, v68, 8, v64
	v_lshlrev_b32_e32 v72, 2, v72
	v_add_u32_e32 v72, 0x1b400, v72
	s_waitcnt lgkmcnt(0)
	ds_write_b32 v72, v70
	ds_write_b32 v72, v71 offset:2048
	s_waitcnt vmcnt(0)
	s_lshl_b32 s24, s0, 12
	s_add_u32 s24, s24, 0x12800
	v_lshrrev_b32_e32 v64, 3, v0
	v_and_b32_e32 v64, 0x1fc, v64
	v_add_u32_e32 v64, s24, v64
	v_lshlrev_b32_e64 v65, v0, 1
	ds_or_b32 v64, v65 offset:0
	v_lshrrev_b32_e32 v64, 3, v1
	v_and_b32_e32 v64, 0x1fc, v64
	v_add_u32_e32 v64, s24, v64
	v_lshlrev_b32_e64 v65, v1, 1
	ds_or_b32 v64, v65 offset:512
	v_lshrrev_b32_e32 v64, 3, v2
	v_and_b32_e32 v64, 0x1fc, v64
	v_add_u32_e32 v64, s24, v64
	v_lshlrev_b32_e64 v65, v2, 1
	ds_or_b32 v64, v65 offset:1024
	v_lshrrev_b32_e32 v64, 3, v3
	v_and_b32_e32 v64, 0x1fc, v64
	v_add_u32_e32 v64, s24, v64
	v_lshlrev_b32_e64 v65, v3, 1
	ds_or_b32 v64, v65 offset:1536
	v_lshrrev_b32_e32 v64, 3, v4
	v_and_b32_e32 v64, 0x1fc, v64
	v_add_u32_e32 v64, s24, v64
	v_lshlrev_b32_e64 v65, v4, 1
	ds_or_b32 v64, v65 offset:2048
	v_lshrrev_b32_e32 v64, 3, v5
	v_and_b32_e32 v64, 0x1fc, v64
	v_add_u32_e32 v64, s24, v64
	v_lshlrev_b32_e64 v65, v5, 1
	ds_or_b32 v64, v65 offset:2560
	v_lshrrev_b32_e32 v64, 3, v6
	v_and_b32_e32 v64, 0x1fc, v64
	v_add_u32_e32 v64, s24, v64
	v_lshlrev_b32_e64 v65, v6, 1
	ds_or_b32 v64, v65 offset:3072
	v_lshrrev_b32_e32 v64, 3, v7
	v_and_b32_e32 v64, 0x1fc, v64
	v_add_u32_e32 v64, s24, v64
	v_lshlrev_b32_e64 v65, v7, 1
	ds_or_b32 v64, v65 offset:3584
	s_cmp_gt_u32 s43, 1
	s_cbranch_scc0 .Ldsa_selor_end
; #define LAS __attribute__((address_space(3)))
; #define LDS_WAIT() asm volatile("s_waitcnt lgkmcnt(0)" ::: "memory")
; __device__ __forceinline__ void dsa_unit(const bf16* QB, const int* SEL, bf16* AO, int b, int kvh, int t, LAS unsigned char* wl, int lane) {
;     ...
;     for (int kb = 0; kb < 8; ++kb) {
; #pragma unroll
;         for (int i = 0; i < 8; ++i) *(LAS bf16x8*)(kdst + (4 * i) * 272) = kr[kb % 3][i];
;         if (kb + 3 < 8) {
; #pragma unroll
;             for (int i = 0; i < 8; ++i) kr[kb % 3][i] = *(const bf16x8*)(kg + (size_t)il[32 * (kb + 3) + 4 * i + r4] * NBP);
;         }
;         LDS_WAIT();
;         f32x4v a0 = {0.f, 0.f, 0.f, 0.f}, a1 = {0.f, 0.f, 0.f, 0.f};
	v_lshrrev_b32_e32 v64, 3, v8
	v_and_b32_e32 v64, 0x1fc, v64
	v_add_u32_e32 v64, s24, v64
	v_lshlrev_b32_e64 v65, v8, 1
	ds_or_b32 v64, v65 offset:0
	v_lshrrev_b32_e32 v64, 3, v9
	v_and_b32_e32 v64, 0x1fc, v64
	v_add_u32_e32 v64, s24, v64
	v_lshlrev_b32_e64 v65, v9, 1
	ds_or_b32 v64, v65 offset:512
	v_lshrrev_b32_e32 v64, 3, v10
	v_and_b32_e32 v64, 0x1fc, v64
	v_add_u32_e32 v64, s24, v64
	v_lshlrev_b32_e64 v65, v10, 1
	ds_or_b32 v64, v65 offset:1024
	v_lshrrev_b32_e32 v64, 3, v11
	v_and_b32_e32 v64, 0x1fc, v64
	v_add_u32_e32 v64, s24, v64
	v_lshlrev_b32_e64 v65, v11, 1
	ds_or_b32 v64, v65 offset:1536
	v_lshrrev_b32_e32 v64, 3, v12
	v_and_b32_e32 v64, 0x1fc, v64
	v_add_u32_e32 v64, s24, v64
	v_lshlrev_b32_e64 v65, v12, 1
	ds_or_b32 v64, v65 offset:2048
	v_lshrrev_b32_e32 v64, 3, v13
	v_and_b32_e32 v64, 0x1fc, v64
	v_add_u32_e32 v64, s24, v64
	v_lshlrev_b32_e64 v65, v13, 1
	ds_or_b32 v64, v65 offset:2560
	v_lshrrev_b32_e32 v64, 3, v14
	v_and_b32_e32 v64, 0x1fc, v64
	v_add_u32_e32 v64, s24, v64
	v_lshlrev_b32_e64 v65, v14, 1
	ds_or_b32 v64, v65 offset:3072
	v_lshrrev_b32_e32 v64, 3, v15
	v_and_b32_e32 v64, 0x1fc, v64
	v_add_u32_e32 v64, s24, v64
	v_lshlrev_b32_e64 v65, v15, 1
	ds_or_b32 v64, v65 offset:3584
	s_cmp_gt_u32 s43, 2
	s_cbranch_scc0 .Ldsa_selor_end
	v_lshrrev_b32_e32 v64, 3, v16
	v_and_b32_e32 v64, 0x1fc, v64
	v_add_u32_e32 v64, s24, v64
	v_lshlrev_b32_e64 v65, v16, 1
	ds_or_b32 v64, v65 offset:0
	v_lshrrev_b32_e32 v64, 3, v17
	v_and_b32_e32 v64, 0x1fc, v64
	v_add_u32_e32 v64, s24, v64
	v_lshlrev_b32_e64 v65, v17, 1
	ds_or_b32 v64, v65 offset:512
	v_lshrrev_b32_e32 v64, 3, v18
	v_and_b32_e32 v64, 0x1fc, v64
	v_add_u32_e32 v64, s24, v64
	v_lshlrev_b32_e64 v65, v18, 1
	ds_or_b32 v64, v65 offset:1024
	v_lshrrev_b32_e32 v64, 3, v19
	v_and_b32_e32 v64, 0x1fc, v64
	v_add_u32_e32 v64, s24, v64
	v_lshlrev_b32_e64 v65, v19, 1
	ds_or_b32 v64, v65 offset:1536
	v_lshrrev_b32_e32 v64, 3, v20
	v_and_b32_e32 v64, 0x1fc, v64
	v_add_u32_e32 v64, s24, v64
	v_lshlrev_b32_e64 v65, v20, 1
	ds_or_b32 v64, v65 offset:2048
	v_lshrrev_b32_e32 v64, 3, v21
	v_and_b32_e32 v64, 0x1fc, v64
	v_add_u32_e32 v64, s24, v64
	v_lshlrev_b32_e64 v65, v21, 1
	ds_or_b32 v64, v65 offset:2560
	v_lshrrev_b32_e32 v64, 3, v22
	v_and_b32_e32 v64, 0x1fc, v64
	v_add_u32_e32 v64, s24, v64
	v_lshlrev_b32_e64 v65, v22, 1
	ds_or_b32 v64, v65 offset:3072
	v_lshrrev_b32_e32 v64, 3, v23
	v_and_b32_e32 v64, 0x1fc, v64
	v_add_u32_e32 v64, s24, v64
	v_lshlrev_b32_e64 v65, v23, 1
	ds_or_b32 v64, v65 offset:3584
	s_cmp_gt_u32 s43, 3
	s_cbranch_scc0 .Ldsa_selor_end
	v_lshrrev_b32_e32 v64, 3, v24
	v_and_b32_e32 v64, 0x1fc, v64
	v_add_u32_e32 v64, s24, v64
	v_lshlrev_b32_e64 v65, v24, 1
	ds_or_b32 v64, v65 offset:0
	v_lshrrev_b32_e32 v64, 3, v25
	v_and_b32_e32 v64, 0x1fc, v64
	v_add_u32_e32 v64, s24, v64
	v_lshlrev_b32_e64 v65, v25, 1
	ds_or_b32 v64, v65 offset:512
	v_lshrrev_b32_e32 v64, 3, v26
	v_and_b32_e32 v64, 0x1fc, v64
	v_add_u32_e32 v64, s24, v64
	v_lshlrev_b32_e64 v65, v26, 1
	ds_or_b32 v64, v65 offset:1024
	v_lshrrev_b32_e32 v64, 3, v27
	v_and_b32_e32 v64, 0x1fc, v64
	v_add_u32_e32 v64, s24, v64
	v_lshlrev_b32_e64 v65, v27, 1
	ds_or_b32 v64, v65 offset:1536
	v_lshrrev_b32_e32 v64, 3, v28
	v_and_b32_e32 v64, 0x1fc, v64
	v_add_u32_e32 v64, s24, v64
	v_lshlrev_b32_e64 v65, v28, 1
	ds_or_b32 v64, v65 offset:2048
	v_lshrrev_b32_e32 v64, 3, v29
	v_and_b32_e32 v64, 0x1fc, v64
	v_add_u32_e32 v64, s24, v64
	v_lshlrev_b32_e64 v65, v29, 1
	ds_or_b32 v64, v65 offset:2560
	v_lshrrev_b32_e32 v64, 3, v30
	v_and_b32_e32 v64, 0x1fc, v64
	v_add_u32_e32 v64, s24, v64
	v_lshlrev_b32_e64 v65, v30, 1
	ds_or_b32 v64, v65 offset:3072
	v_lshrrev_b32_e32 v64, 3, v31
	v_and_b32_e32 v64, 0x1fc, v64
	v_add_u32_e32 v64, s24, v64
	v_lshlrev_b32_e64 v65, v31, 1
	ds_or_b32 v64, v65 offset:3584
.Ldsa_selor_end:
	s_barrier
	ds_write_b128 v166, v[144:147]
	ds_write_b128 v167, v[148:151]
	ds_write_b128 v166, v[152:155] offset:8704
	ds_write_b128 v167, v[156:159] offset:10240
	v_mov_b32_e32 v0, 0
	v_mov_b32_e32 v1, 0
	v_mov_b32_e32 v2, 0
	v_mov_b32_e32 v3, 0
	v_mov_b32_e32 v4, 0
	v_mov_b32_e32 v5, 0
	v_mov_b32_e32 v6, 0
	v_mov_b32_e32 v7, 0
	v_mov_b32_e32 v8, 0
	v_mov_b32_e32 v9, 0
	v_mov_b32_e32 v10, 0
	v_mov_b32_e32 v11, 0
	v_mov_b32_e32 v12, 0
	v_mov_b32_e32 v13, 0
	v_mov_b32_e32 v14, 0
	v_mov_b32_e32 v15, 0
	v_mov_b32_e32 v16, 0
	v_mov_b32_e32 v17, 0
	v_mov_b32_e32 v18, 0
	v_mov_b32_e32 v19, 0
	v_mov_b32_e32 v20, 0
	v_mov_b32_e32 v21, 0
	v_mov_b32_e32 v22, 0
	v_mov_b32_e32 v23, 0
	v_mov_b32_e32 v24, 0
	v_mov_b32_e32 v25, 0
	v_mov_b32_e32 v26, 0
	v_mov_b32_e32 v27, 0
	v_mov_b32_e32 v28, 0
	v_mov_b32_e32 v29, 0
	v_mov_b32_e32 v30, 0
	v_mov_b32_e32 v31, 0
	v_mov_b32_e32 v32, 0
	v_mov_b32_e32 v33, 0
	v_mov_b32_e32 v34, 0
	v_mov_b32_e32 v35, 0
	v_mov_b32_e32 v36, 0
	v_mov_b32_e32 v37, 0
	v_mov_b32_e32 v38, 0
	v_mov_b32_e32 v39, 0
	v_mov_b32_e32 v40, 0
	v_mov_b32_e32 v41, 0
	v_mov_b32_e32 v42, 0
	v_mov_b32_e32 v43, 0
	v_mov_b32_e32 v44, 0
	v_mov_b32_e32 v45, 0
	v_mov_b32_e32 v46, 0
	v_mov_b32_e32 v47, 0
	v_mov_b32_e32 v48, 0
	v_mov_b32_e32 v49, 0
	v_mov_b32_e32 v50, 0
	v_mov_b32_e32 v51, 0
	v_mov_b32_e32 v52, 0
	v_mov_b32_e32 v53, 0
	v_mov_b32_e32 v54, 0
	v_mov_b32_e32 v55, 0
	v_mov_b32_e32 v56, 0
	v_mov_b32_e32 v57, 0
	v_mov_b32_e32 v58, 0
	v_mov_b32_e32 v59, 0
	v_mov_b32_e32 v60, 0
	v_mov_b32_e32 v61, 0
	v_mov_b32_e32 v62, 0
	v_mov_b32_e32 v63, 0
	v_mov_b32_e32 v173, 0
	s_mov_b32 s9, 0
	s_mov_b32 s10, 0
	s_mov_b32 s11, 0x9400
	s_waitcnt lgkmcnt(0)
	s_barrier
	s_mov_b32 s13, 0xf149f2ca
	ds_read_b32 v174, v172
	ds_read_b32 v182, v172 offset:4
	s_waitcnt lgkmcnt(0)
	v_lshrrev_b32_e32 v174, v175, v174
	v_bfe_i32 v178, v174, 0, 1
	v_bfi_b32 v64, v178, v176, s13
	v_bfe_i32 v179, v174, 1, 1
	v_bfi_b32 v65, v179, v176, s13
	v_bfe_i32 v178, v174, 2, 1
	v_bfi_b32 v66, v178, v176, s13
	v_bfe_i32 v179, v174, 3, 1
	v_bfi_b32 v67, v179, v176, s13
	v_bfe_i32 v178, v174, 4, 1
	v_bfi_b32 v68, v178, v176, s13
	v_bfe_i32 v179, v174, 5, 1
	v_bfi_b32 v69, v179, v176, s13
	v_bfe_i32 v178, v174, 6, 1
	v_bfi_b32 v70, v178, v176, s13
	v_bfe_i32 v179, v174, 7, 1
	v_bfi_b32 v71, v179, v176, s13
	v_bfe_i32 v178, v174, 16, 1
	v_bfi_b32 v72, v178, v176, s13
	v_bfe_i32 v179, v174, 17, 1
	v_bfi_b32 v73, v179, v176, s13
	v_bfe_i32 v178, v174, 18, 1
	v_bfi_b32 v74, v178, v176, s13
	v_bfe_i32 v179, v174, 19, 1
	v_bfi_b32 v75, v179, v176, s13
	v_bfe_i32 v178, v174, 20, 1
	v_bfi_b32 v76, v178, v176, s13
	v_bfe_i32 v179, v174, 21, 1
	v_bfi_b32 v77, v179, v176, s13
	v_bfe_i32 v178, v174, 22, 1
	v_bfi_b32 v78, v178, v176, s13
	v_bfe_i32 v179, v174, 23, 1
	v_bfi_b32 v79, v179, v176, s13

; #define LAS __attribute__((address_space(3)))
; __device__ __forceinline__ unsigned pk2(float lo, float hi) { return pg8::cvt_pk_bf16(lo, hi); }
; #define LDS_WAIT() asm volatile("s_waitcnt lgkmcnt(0)" ::: "memory")
; __device__ __forceinline__ s16x4 vtr(const LAS unsigned char* p) { return __builtin_bit_cast(s16x4, __builtin_amdgcn_ds_read_tr16_b64_v4i16((LAS s16x4*)p)); }
; __device__ __forceinline__ void dsa_unit(const bf16* QB, const int* SEL, bf16* AO, int b, int kvh, int t, LAS unsigned char* wl, int lane) {
;     ...
;     for (int g = 0; g < 4; ++g) {
;         float m = mx[g];
;         m = __builtin_fmaxf(m, __shfl_xor(m, 1)); m = __builtin_fmaxf(m, __shfl_xor(m, 2)); m = __builtin_fmaxf(m, __shfl_xor(m, 4)); m = __builtin_fmaxf(m, __shfl_xor(m, 8)); m = __builtin_fmaxf(m, __shfl_xor(m, 16));
;         float s = 0.f;
; #pragma unroll
;         for (int kb = 0; kb < 8; ++kb) { const float e = __builtin_amdgcn_exp2f(lg[kb][g] - m); lg[kb][g] = e; s += e; }
;         s += __shfl_xor(s, 1); s += __shfl_xor(s, 2); s += __shfl_xor(s, 4); s += __shfl_xor(s, 8); s += __shfl_xor(s, 16);
;         const float inv = 1.0f / s;
; #pragma unroll
;         for (int kb = 0; kb < 8; ++kb) if ((kb >> 2) == hi) pT[g * 256 + 32 * kb + n] = (bf16)(pk2(lg[kb][g] * inv, 0.f) & 0xffffu);
;     }
;     f32x4v o[8];
; #pragma unroll
;     for (int c = 0; c < 8; ++c) o[c] = (f32x4v){0.f, 0.f, 0.f, 0.f};
;     const LAS unsigned char* vtb = buf + (8 * kq + (l15 >> 2)) * 288 + (lane & 3) * 8;
;     LAS unsigned char* vdst = buf + r4 * 288 + c16 * 16;
;     const LAS bf16* pfp = pT + (l15 & 3) * 256 + 8 * kq;
; #pragma unroll
;     for (int ch = 0; ch < 8; ++ch) {
; #pragma unroll
;         for (int i = 0; i < 8; ++i) *(LAS bf16x8*)(vdst + (4 * i) * 288) = vr[ch % 3][i];
;         if (ch + 3 < 8) {
; #pragma unroll
;             for (int i = 0; i < 8; ++i) vr[ch % 3][i] = *(const bf16x8*)(vg + (size_t)il[32 * (ch + 3) + 4 * i + r4] * NBP);
;         }
;         const bf16x8 pf = *(const LAS bf16x8*)(pfp + 32 * ch);
;         LDS_WAIT();
; #pragma unroll
;         for (int c = 0; c < 8; ++c) {
;             const s16x4 lo = vtr(vtb + c * 32), hh = vtr(vtb + 4 * 288 + c * 32);
;             o[c] = __builtin_amdgcn_mfma_f32_16x16x32_bf16(pf, (bf16x8){lo[0], lo[1], lo[2], lo[3], hh[0], hh[1], hh[2], hh[3]}, o[c], 0, 0, 0);
;         }
;         LDS_WAIT();
;     }
.Ldsa_farB:
	ds_read_b32 v174, v172 offset:8
	ds_read_b32 v182, v172 offset:12
	s_nop 1
	s_waitcnt lgkmcnt(5)
	v_mfma_f32_32x32x16_bf16 v[128:143], v[112:115], v[80:83], v[128:143]
	ds_read_b128 v[112:115], v168 offset:8832
	v_exp_f32_e32 v64, v64
	v_exp_f32_e32 v65, v65
	v_add_f32_e32 v173, v173, v64
	v_add_f32_e32 v173, v173, v65
	v_cvt_pk_bf16_f32 v64, v64, v65
	s_waitcnt lgkmcnt(5)
	v_mfma_f32_32x32x16_bf16 v[128:143], v[116:119], v[84:87], v[128:143]
	ds_read_b128 v[116:119], v168 offset:8864
	v_exp_f32_e32 v66, v66
	v_exp_f32_e32 v67, v67
	v_add_f32_e32 v173, v173, v66
	v_add_f32_e32 v173, v173, v67
	v_cvt_pk_bf16_f32 v65, v66, v67
	s_waitcnt lgkmcnt(5)
	v_mfma_f32_32x32x16_bf16 v[128:143], v[120:123], v[88:91], v[128:143]
	ds_read_b128 v[120:123], v168 offset:8896
	v_exp_f32_e32 v68, v68
	v_exp_f32_e32 v69, v69
	v_add_f32_e32 v173, v173, v68
	v_add_f32_e32 v173, v173, v69
	v_cvt_pk_bf16_f32 v66, v68, v69
	s_waitcnt lgkmcnt(5)
	v_mfma_f32_32x32x16_bf16 v[128:143], v[124:127], v[92:95], v[128:143]
	ds_read_b128 v[124:127], v168 offset:8928
	v_exp_f32_e32 v70, v70
	v_exp_f32_e32 v71, v71
	v_add_f32_e32 v173, v173, v70
	v_add_f32_e32 v173, v173, v71
	v_cvt_pk_bf16_f32 v67, v70, v71
	s_waitcnt lgkmcnt(3)
	v_mfma_f32_32x32x16_bf16 v[128:143], v[112:115], v[96:99], v[128:143]
	ds_read_b64_tr_b16 v[112:113], v169 offset:0
	ds_read_b64_tr_b16 v[114:115], v169 offset:1280
	v_exp_f32_e32 v72, v72
	v_exp_f32_e32 v73, v73
	v_add_f32_e32 v173, v173, v72
	v_add_f32_e32 v173, v173, v73
	v_cvt_pk_bf16_f32 v68, v72, v73
	s_waitcnt lgkmcnt(4)
	v_mfma_f32_32x32x16_bf16 v[128:143], v[116:119], v[100:103], v[128:143]
	ds_read_b64_tr_b16 v[116:117], v169 offset:64
	ds_read_b64_tr_b16 v[118:119], v169 offset:1344
	v_exp_f32_e32 v74, v74
	v_exp_f32_e32 v75, v75
	v_add_f32_e32 v173, v173, v74
	v_add_f32_e32 v173, v173, v75
	v_cvt_pk_bf16_f32 v69, v74, v75
	s_waitcnt lgkmcnt(5)
	v_mfma_f32_32x32x16_bf16 v[128:143], v[120:123], v[104:107], v[128:143]
	ds_read_b64_tr_b16 v[120:121], v169 offset:128
	ds_read_b64_tr_b16 v[122:123], v169 offset:1408
	v_exp_f32_e32 v76, v76
	v_exp_f32_e32 v77, v77
	v_add_f32_e32 v173, v173, v76
	v_add_f32_e32 v173, v173, v77
	v_cvt_pk_bf16_f32 v70, v76, v77
	s_waitcnt lgkmcnt(6)
	v_mfma_f32_32x32x16_bf16 v[128:143], v[124:127], v[108:111], v[128:143]
	ds_read_b64_tr_b16 v[124:125], v169 offset:192
	ds_read_b64_tr_b16 v[126:127], v169 offset:1472
	v_exp_f32_e32 v78, v78
	v_exp_f32_e32 v79, v79
	v_add_f32_e32 v173, v173, v78
	v_add_f32_e32 v173, v173, v79
	v_cvt_pk_bf16_f32 v71, v78, v79
	s_waitcnt lgkmcnt(6)
	v_mfma_f32_32x32x16_bf16 v[0:15], v[64:67], v[112:115], v[0:15]
	ds_read_b64_tr_b16 v[112:113], v169 offset:5120
	ds_read_b64_tr_b16 v[114:115], v169 offset:6400
	s_waitcnt vmcnt(0)
	ds_write_b128 v170, v[144:147]
	v_exp_f32_e32 v128, v128
	v_exp_f32_e32 v129, v129
	v_add_f32_e32 v173, v173, v128
	v_add_f32_e32 v173, v173, v129
	v_cvt_pk_bf16_f32 v128, v128, v129
	s_waitcnt lgkmcnt(7)
	v_mfma_f32_32x32x16_bf16 v[16:31], v[64:67], v[116:119], v[16:31]
	ds_read_b64_tr_b16 v[116:117], v169 offset:5184
	ds_read_b64_tr_b16 v[118:119], v169 offset:6464
	ds_write_b128 v171, v[148:151]
	v_exp_f32_e32 v130, v130
	v_exp_f32_e32 v131, v131
	v_add_f32_e32 v173, v173, v130
	v_add_f32_e32 v173, v173, v131
	v_cvt_pk_bf16_f32 v129, v130, v131
	s_waitcnt lgkmcnt(8)
	v_mfma_f32_32x32x16_bf16 v[32:47], v[64:67], v[120:123], v[32:47]
	ds_read_b64_tr_b16 v[120:121], v169 offset:5248
	ds_read_b64_tr_b16 v[122:123], v169 offset:6528
	ds_write_b128 v170, v[152:155] offset:8704
	v_exp_f32_e32 v132, v132
	v_exp_f32_e32 v133, v133
	v_add_f32_e32 v173, v173, v132
	v_add_f32_e32 v173, v173, v133
	v_cvt_pk_bf16_f32 v130, v132, v133
	s_waitcnt lgkmcnt(9)
	v_mfma_f32_32x32x16_bf16 v[48:63], v[64:67], v[124:127], v[48:63]
	ds_read_b64_tr_b16 v[124:125], v169 offset:5312
	ds_read_b64_tr_b16 v[126:127], v169 offset:6592
	ds_write_b128 v171, v[156:159] offset:10240
	v_exp_f32_e32 v134, v134
	v_exp_f32_e32 v135, v135
	v_add_f32_e32 v173, v173, v134
	v_add_f32_e32 v173, v173, v135
	v_cvt_pk_bf16_f32 v131, v134, v135
	s_waitcnt lgkmcnt(10)
	v_mfma_f32_32x32x16_bf16 v[0:15], v[68:71], v[112:115], v[0:15]
	ds_read_b64_tr_b16 v[112:113], v169 offset:10240
	ds_read_b64_tr_b16 v[114:115], v169 offset:11520
	s_nop 0
	v_exp_f32_e32 v136, v136
	v_exp_f32_e32 v137, v137
	v_add_f32_e32 v173, v173, v136
	v_add_f32_e32 v173, v173, v137
	v_cvt_pk_bf16_f32 v132, v136, v137
	s_waitcnt lgkmcnt(9)
	v_mfma_f32_32x32x16_bf16 v[16:31], v[68:71], v[116:119], v[16:31]
	ds_read_b64_tr_b16 v[116:117], v169 offset:10304
	ds_read_b64_tr_b16 v[118:119], v169 offset:11584
	s_nop 0
	v_exp_f32_e32 v138, v138
	v_exp_f32_e32 v139, v139
	v_add_f32_e32 v173, v173, v138
	v_add_f32_e32 v173, v173, v139
	v_cvt_pk_bf16_f32 v133, v138, v139
	s_waitcnt lgkmcnt(8)
	v_mfma_f32_32x32x16_bf16 v[32:47], v[68:71], v[120:123], v[32:47]
	ds_read_b64_tr_b16 v[120:121], v169 offset:10368
	ds_read_b64_tr_b16 v[122:123], v169 offset:11648
	s_nop 0
	v_exp_f32_e32 v140, v140
	v_exp_f32_e32 v141, v141
	v_add_f32_e32 v173, v173, v140
	v_add_f32_e32 v173, v173, v141
	v_cvt_pk_bf16_f32 v134, v140, v141
	s_waitcnt lgkmcnt(7)
	v_mfma_f32_32x32x16_bf16 v[48:63], v[68:71], v[124:127], v[48:63]
	ds_read_b64_tr_b16 v[124:125], v169 offset:10432
	ds_read_b64_tr_b16 v[126:127], v169 offset:11712
	s_nop 0
	v_exp_f32_e32 v142, v142
	v_exp_f32_e32 v143, v143
	v_add_f32_e32 v173, v173, v142
	v_add_f32_e32 v173, v173, v143
	v_cvt_pk_bf16_f32 v135, v142, v143
	v_lshrrev_b32_e32 v174, v175, v174
	s_waitcnt lgkmcnt(6)
; #define LAS __attribute__((address_space(3)))
; __device__ __forceinline__ unsigned pk2(float lo, float hi) { return pg8::cvt_pk_bf16(lo, hi); }
; #define LDS_WAIT() asm volatile("s_waitcnt lgkmcnt(0)" ::: "memory")
; __device__ __forceinline__ s16x4 vtr(const LAS unsigned char* p) { return __builtin_bit_cast(s16x4, __builtin_amdgcn_ds_read_tr16_b64_v4i16((LAS s16x4*)p)); }
; __device__ __forceinline__ void dsa_unit(const bf16* QB, const int* SEL, bf16* AO, int b, int kvh, int t, LAS unsigned char* wl, int lane) {
;     ...
;     for (int ch = 0; ch < 8; ++ch) {
; #pragma unroll
;         for (int i = 0; i < 8; ++i) *(LAS bf16x8*)(vdst + (4 * i) * 288) = vr[ch % 3][i];
;         if (ch + 3 < 8) {
; #pragma unroll
;             for (int i = 0; i < 8; ++i) vr[ch % 3][i] = *(const bf16x8*)(vg + (size_t)il[32 * (ch + 3) + 4 * i + r4] * NBP);
;         }
;         const bf16x8 pf = *(const LAS bf16x8*)(pfp + 32 * ch);
;         LDS_WAIT();
; #pragma unroll
;         for (int c = 0; c < 8; ++c) {
;             const s16x4 lo = vtr(vtb + c * 32), hh = vtr(vtb + 4 * 288 + c * 32);
;             o[c] = __builtin_amdgcn_mfma_f32_16x16x32_bf16(pf, (bf16x8){lo[0], lo[1], lo[2], lo[3], hh[0], hh[1], hh[2], hh[3]}, o[c], 0, 0, 0);
;         }
;         LDS_WAIT();
;     }
;     bf16* op = AO + row * D + (kvh * 4) * 128 + 16 * kq + l15;
; #pragma unroll
;     for (int i = 0; i < 2; ++i)
; #pragma unroll
;         for (int g = 0; g < 4; ++g) {
;             const float v = (kq == 0) ? o[4 * i][g] : (kq == 1) ? o[4 * i + 1][g] : (kq == 2) ? o[4 * i + 2][g] : o[4 * i + 3][g];
;             op[g * 128 + 64 * i] = (bf16)(pk2(v, 0.f) & 0xffffu);
;         }
	v_mfma_f32_32x32x16_bf16 v[0:15], v[128:131], v[112:115], v[0:15]
	ds_read_b64_tr_b16 v[112:113], v169 offset:15360
	ds_read_b64_tr_b16 v[114:115], v169 offset:16640
	v_bfe_i32 v178, v174, 0, 1
	v_bfi_b32 v64, v178, v176, s13
	v_bfe_i32 v179, v174, 1, 1
	v_bfi_b32 v65, v179, v176, s13
	s_waitcnt lgkmcnt(6)
	v_mfma_f32_32x32x16_bf16 v[16:31], v[128:131], v[116:119], v[16:31]
	ds_read_b64_tr_b16 v[116:117], v169 offset:15424
	ds_read_b64_tr_b16 v[118:119], v169 offset:16704
	v_bfe_i32 v178, v174, 2, 1
	v_bfi_b32 v66, v178, v176, s13
	v_bfe_i32 v179, v174, 3, 1
	v_bfi_b32 v67, v179, v176, s13
	s_waitcnt lgkmcnt(6)
	v_mfma_f32_32x32x16_bf16 v[32:47], v[128:131], v[120:123], v[32:47]
	ds_read_b64_tr_b16 v[120:121], v169 offset:15488
	ds_read_b64_tr_b16 v[122:123], v169 offset:16768
	v_bfe_i32 v178, v174, 4, 1
	v_bfi_b32 v68, v178, v176, s13
	v_bfe_i32 v179, v174, 5, 1
	v_bfi_b32 v69, v179, v176, s13
	s_waitcnt lgkmcnt(6)
	v_mfma_f32_32x32x16_bf16 v[48:63], v[128:131], v[124:127], v[48:63]
	ds_read_b64_tr_b16 v[124:125], v169 offset:15552
	ds_read_b64_tr_b16 v[126:127], v169 offset:16832
	v_bfe_i32 v178, v174, 6, 1
	v_bfi_b32 v70, v178, v176, s13
	v_bfe_i32 v179, v174, 7, 1
	v_bfi_b32 v71, v179, v176, s13
	s_waitcnt lgkmcnt(6)
	v_mfma_f32_32x32x16_bf16 v[0:15], v[132:135], v[112:115], v[0:15]
	v_bfe_i32 v178, v174, 16, 1
	v_bfi_b32 v72, v178, v176, s13
	v_bfe_i32 v179, v174, 17, 1
	v_bfi_b32 v73, v179, v176, s13
	s_waitcnt lgkmcnt(4)
	v_mfma_f32_32x32x16_bf16 v[16:31], v[132:135], v[116:119], v[16:31]
	v_bfe_i32 v178, v174, 18, 1
	v_bfi_b32 v74, v178, v176, s13
	v_bfe_i32 v179, v174, 19, 1
	v_bfi_b32 v75, v179, v176, s13
	s_waitcnt lgkmcnt(2)
	v_mfma_f32_32x32x16_bf16 v[32:47], v[132:135], v[120:123], v[32:47]
	v_bfe_i32 v178, v174, 20, 1
	v_bfi_b32 v76, v178, v176, s13
	v_bfe_i32 v179, v174, 21, 1
	v_bfi_b32 v77, v179, v176, s13
	s_waitcnt lgkmcnt(0)
	v_mfma_f32_32x32x16_bf16 v[48:63], v[132:135], v[124:127], v[48:63]
	v_bfe_i32 v178, v174, 22, 1
	v_bfi_b32 v78, v178, v176, s13
	v_bfe_i32 v179, v174, 23, 1
	v_bfi_b32 v79, v179, v176, s13
	s_waitcnt lgkmcnt(0)
	s_barrier
	s_mov_b32 s25, s10
	s_mov_b32 s10, s11
	s_mov_b32 s11, s25
	v_add_u32_e32 v172, 8, v172
	s_mov_b32 s9, s24
	s_cmp_lt_u32 s9, s8
	s_cbranch_scc1 .Ldsa_it
	v_xor_b32_e32 v178, 32, v206
	v_lshlrev_b32_e32 v178, 2, v178
	ds_bpermute_b32 v179, v178, v173
	s_waitcnt lgkmcnt(0)
	v_add_f32_e32 v173, v173, v179
	v_rcp_f32_e32 v173, v173
	s_nop 0
	v_and_b32_e32 v178, 31, v206
	v_lshlrev_b32_e32 v178, 2, v178
	s_lshl_b32 s24, s0, 7
	s_add_u32 s24, s24, 0x1b000
	v_add_u32_e32 v178, s24, v178
	ds_write_b32 v178, v173
	v_lshl_add_u32 v179, v175, 1, s24
	s_waitcnt lgkmcnt(0)
	ds_read_b128 v[112:115], v179 offset:0
	ds_read_b128 v[116:119], v179 offset:32
	ds_read_b128 v[120:123], v179 offset:64
	ds_read_b128 v[124:127], v179 offset:96
	v_and_b32_e32 v178, 31, v206
	v_lshlrev_b32_e32 v178, 1, v178
	v_mul_u32_u24_e32 v179, 0x88, v175
	v_add3_u32 v178, v178, v179, s45
	v_lshrrev_b32_e32 v179, 4, v206
	v_mul_u32_u24_e32 v182, 0x110, v179
	v_and_b32_e32 v172, 15, v206
	v_lshl_add_u32 v182, v172, 4, v182
	v_add_u32_e32 v174, s45, v182
	s_add_u32 s24, s44, s7
	s_add_u32 s24, s24, s4
	s_lshr_b32 s25, s24, 20
	s_lshl_b32 s24, s24, 12
	s_add_u32 s24, s24, s67
	s_addc_u32 s25, s25, s85
	s_lshl_b32 s26, s5, 10
	s_add_u32 s24, s24, s26
	s_addc_u32 s25, s25, 0
	v_lshlrev_b32_e32 v179, 8, v179
	v_lshl_add_u32 v182, v172, 4, v179
	v_lshl_add_u64 v[144:145], s[24:25], 0, v[182:183]
	s_movk_i32 s26, 0x1000
	s_mov_b32 s27, 0
	s_waitcnt lgkmcnt(0)
; __device__ __forceinline__ unsigned pk2(float lo, float hi) { return pg8::cvt_pk_bf16(lo, hi); }
; __device__ __forceinline__ void dsa_unit(const bf16* QB, const int* SEL, bf16* AO, int b, int kvh, int t, LAS unsigned char* wl, int lane) {
;     ...
;     bf16* op = AO + row * D + (kvh * 4) * 128 + 16 * kq + l15;
; #pragma unroll
;     for (int i = 0; i < 2; ++i)
; #pragma unroll
;         for (int g = 0; g < 4; ++g) {
;             const float v = (kq == 0) ? o[4 * i][g] : (kq == 1) ? o[4 * i + 1][g] : (kq == 2) ? o[4 * i + 2][g] : o[4 * i + 3][g];
;             op[g * 128 + 64 * i] = (bf16)(pk2(v, 0.f) & 0xffffu);
;         }
	v_pk_mul_f32 v[0:1], v[0:1], v[112:113]
	v_pk_mul_f32 v[2:3], v[2:3], v[114:115]
	v_pk_mul_f32 v[4:5], v[4:5], v[116:117]
	v_pk_mul_f32 v[6:7], v[6:7], v[118:119]
	v_pk_mul_f32 v[8:9], v[8:9], v[120:121]
	v_pk_mul_f32 v[10:11], v[10:11], v[122:123]
	v_pk_mul_f32 v[12:13], v[12:13], v[124:125]
	v_pk_mul_f32 v[14:15], v[14:15], v[126:127]
	v_pk_mul_f32 v[16:17], v[16:17], v[112:113]
	v_pk_mul_f32 v[18:19], v[18:19], v[114:115]
	v_pk_mul_f32 v[20:21], v[20:21], v[116:117]
	v_pk_mul_f32 v[22:23], v[22:23], v[118:119]
	v_pk_mul_f32 v[24:25], v[24:25], v[120:121]
	v_pk_mul_f32 v[26:27], v[26:27], v[122:123]
	v_pk_mul_f32 v[28:29], v[28:29], v[124:125]
	v_pk_mul_f32 v[30:31], v[30:31], v[126:127]
	v_pk_mul_f32 v[32:33], v[32:33], v[112:113]
	v_pk_mul_f32 v[34:35], v[34:35], v[114:115]
	v_pk_mul_f32 v[36:37], v[36:37], v[116:117]
	v_pk_mul_f32 v[38:39], v[38:39], v[118:119]
	v_pk_mul_f32 v[40:41], v[40:41], v[120:121]
	v_pk_mul_f32 v[42:43], v[42:43], v[122:123]
	v_pk_mul_f32 v[44:45], v[44:45], v[124:125]
	v_pk_mul_f32 v[46:47], v[46:47], v[126:127]
	v_pk_mul_f32 v[48:49], v[48:49], v[112:113]
	v_pk_mul_f32 v[50:51], v[50:51], v[114:115]
	v_pk_mul_f32 v[52:53], v[52:53], v[116:117]
	v_pk_mul_f32 v[54:55], v[54:55], v[118:119]
	v_pk_mul_f32 v[56:57], v[56:57], v[120:121]
	v_pk_mul_f32 v[58:59], v[58:59], v[122:123]
	v_pk_mul_f32 v[60:61], v[60:61], v[124:125]
	v_pk_mul_f32 v[62:63], v[62:63], v[126:127]
	v_cvt_pk_bf16_f32 v64, v0, v1
	v_cvt_pk_bf16_f32 v65, v2, v3
	v_cvt_pk_bf16_f32 v66, v4, v5
	v_cvt_pk_bf16_f32 v67, v6, v7
	v_cvt_pk_bf16_f32 v68, v8, v9
	v_cvt_pk_bf16_f32 v69, v10, v11
	v_cvt_pk_bf16_f32 v70, v12, v13
	v_cvt_pk_bf16_f32 v71, v14, v15
	ds_write_b16 v178, v64 offset:0
	ds_write_b16_d16_hi v178, v64 offset:272
	ds_write_b16 v178, v65 offset:544
	ds_write_b16_d16_hi v178, v65 offset:816
	ds_write_b16 v178, v66 offset:2176
	ds_write_b16_d16_hi v178, v66 offset:2448
	ds_write_b16 v178, v67 offset:2720
	ds_write_b16_d16_hi v178, v67 offset:2992
	ds_write_b16 v178, v68 offset:4352
	ds_write_b16_d16_hi v178, v68 offset:4624
	ds_write_b16 v178, v69 offset:4896
	ds_write_b16_d16_hi v178, v69 offset:5168
	ds_write_b16 v178, v70 offset:6528
	ds_write_b16_d16_hi v178, v70 offset:6800
	ds_write_b16 v178, v71 offset:7072
	ds_write_b16_d16_hi v178, v71 offset:7344
	v_cvt_pk_bf16_f32 v72, v16, v17
	v_cvt_pk_bf16_f32 v73, v18, v19
	v_cvt_pk_bf16_f32 v74, v20, v21
	v_cvt_pk_bf16_f32 v75, v22, v23
	v_cvt_pk_bf16_f32 v76, v24, v25
	v_cvt_pk_bf16_f32 v77, v26, v27
	v_cvt_pk_bf16_f32 v78, v28, v29
	v_cvt_pk_bf16_f32 v79, v30, v31
	ds_write_b16 v178, v72 offset:64
	ds_write_b16_d16_hi v178, v72 offset:336
	ds_write_b16 v178, v73 offset:608
	ds_write_b16_d16_hi v178, v73 offset:880
	ds_write_b16 v178, v74 offset:2240
	ds_write_b16_d16_hi v178, v74 offset:2512
	ds_write_b16 v178, v75 offset:2784
	ds_write_b16_d16_hi v178, v75 offset:3056
	ds_write_b16 v178, v76 offset:4416
	ds_write_b16_d16_hi v178, v76 offset:4688
	ds_write_b16 v178, v77 offset:4960
	ds_write_b16_d16_hi v178, v77 offset:5232
	ds_write_b16 v178, v78 offset:6592
	ds_write_b16_d16_hi v178, v78 offset:6864
	ds_write_b16 v178, v79 offset:7136
	ds_write_b16_d16_hi v178, v79 offset:7408
	v_cvt_pk_bf16_f32 v128, v32, v33
	v_cvt_pk_bf16_f32 v129, v34, v35
	v_cvt_pk_bf16_f32 v130, v36, v37
	v_cvt_pk_bf16_f32 v131, v38, v39
	v_cvt_pk_bf16_f32 v132, v40, v41
	v_cvt_pk_bf16_f32 v133, v42, v43
	v_cvt_pk_bf16_f32 v134, v44, v45
	v_cvt_pk_bf16_f32 v135, v46, v47
	ds_write_b16 v178, v128 offset:128
	ds_write_b16_d16_hi v178, v128 offset:400
	ds_write_b16 v178, v129 offset:672
	ds_write_b16_d16_hi v178, v129 offset:944
	ds_write_b16 v178, v130 offset:2304
	ds_write_b16_d16_hi v178, v130 offset:2576
	ds_write_b16 v178, v131 offset:2848
	ds_write_b16_d16_hi v178, v131 offset:3120
	ds_write_b16 v178, v132 offset:4480
	ds_write_b16_d16_hi v178, v132 offset:4752
	ds_write_b16 v178, v133 offset:5024
	ds_write_b16_d16_hi v178, v133 offset:5296
	ds_write_b16 v178, v134 offset:6656
	ds_write_b16_d16_hi v178, v134 offset:6928
	ds_write_b16 v178, v135 offset:7200
	ds_write_b16_d16_hi v178, v135 offset:7472
	v_cvt_pk_bf16_f32 v136, v48, v49
	v_cvt_pk_bf16_f32 v137, v50, v51
	v_cvt_pk_bf16_f32 v138, v52, v53
	v_cvt_pk_bf16_f32 v139, v54, v55
	v_cvt_pk_bf16_f32 v140, v56, v57
	v_cvt_pk_bf16_f32 v141, v58, v59
	v_cvt_pk_bf16_f32 v142, v60, v61
	v_cvt_pk_bf16_f32 v143, v62, v63
	ds_write_b16 v178, v136 offset:192
	ds_write_b16_d16_hi v178, v136 offset:464
	ds_write_b16 v178, v137 offset:736
	ds_write_b16_d16_hi v178, v137 offset:1008
	ds_write_b16 v178, v138 offset:2368
	ds_write_b16_d16_hi v178, v138 offset:2640
	ds_write_b16 v178, v139 offset:2912
	ds_write_b16_d16_hi v178, v139 offset:3184
	ds_write_b16 v178, v140 offset:4544
	ds_write_b16_d16_hi v178, v140 offset:4816
	ds_write_b16 v178, v141 offset:5088
	ds_write_b16_d16_hi v178, v141 offset:5360
	ds_write_b16 v178, v142 offset:6720
	ds_write_b16_d16_hi v178, v142 offset:6992
	ds_write_b16 v178, v143 offset:7264
	ds_write_b16_d16_hi v178, v143 offset:7536
	s_waitcnt lgkmcnt(0)
	ds_read_b128 v[80:83], v174 offset:0
	ds_read_b128 v[84:87], v174 offset:1088
	ds_read_b128 v[88:91], v174 offset:2176
	ds_read_b128 v[92:95], v174 offset:3264
	ds_read_b128 v[96:99], v174 offset:4352
	ds_read_b128 v[100:103], v174 offset:5440
	ds_read_b128 v[104:107], v174 offset:6528
	ds_read_b128 v[108:111], v174 offset:7616
	s_waitcnt lgkmcnt(7)
	global_store_dwordx4 v[144:145], v[80:83], off
	v_lshl_add_u64 v[144:145], v[144:145], 0, s[26:27]
	s_waitcnt lgkmcnt(6)
	global_store_dwordx4 v[144:145], v[84:87], off
	v_lshl_add_u64 v[144:145], v[144:145], 0, s[26:27]
	s_waitcnt lgkmcnt(5)
	global_store_dwordx4 v[144:145], v[88:91], off
	v_lshl_add_u64 v[144:145], v[144:145], 0, s[26:27]
	s_waitcnt lgkmcnt(4)
	global_store_dwordx4 v[144:145], v[92:95], off
	v_lshl_add_u64 v[144:145], v[144:145], 0, s[26:27]
	s_waitcnt lgkmcnt(3)
	global_store_dwordx4 v[144:145], v[96:99], off
	v_lshl_add_u64 v[144:145], v[144:145], 0, s[26:27]
	s_waitcnt lgkmcnt(2)
	global_store_dwordx4 v[144:145], v[100:103], off
	v_lshl_add_u64 v[144:145], v[144:145], 0, s[26:27]
	s_waitcnt lgkmcnt(1)
	global_store_dwordx4 v[144:145], v[104:107], off
	v_lshl_add_u64 v[144:145], v[144:145], 0, s[26:27]
	s_waitcnt lgkmcnt(0)
	global_store_dwordx4 v[144:145], v[108:111], off
	s_add_u32 s21, s21, 1
	s_cmp_lt_u32 s21, 2
	s_cbranch_scc1 .Ldsa_half
	s_add_u32 s3, s3, s2
	s_branch .Ldsa_unit
